# non-temporal (nt) hint on the final f32 output stores of the last FFN-out GEMM epilogue
# speedup vs baseline: 1.0064x; 1.0064x over previous
.LBB0_1276:
	v_mov_b32_e32 v128, v194
	v_mov_b32_e32 v129, v195
	s_lshl_b32 s16, s43, 8
	s_add_i32 s16, s16, s31
	v_add_u32_e32 v128, s16, v128
	s_lshl_b32 s16, s42, 8
	s_or_b32 s16, s16, s34
	v_lshl_add_u32 v130, v129, 3, s16
	v_ashrrev_i32_e32 v131, 31, v130
	v_ashrrev_i32_e32 v129, 31, v128
	v_lshl_add_u64 v[132:133], v[130:131], 1, s[58:59]
	v_lshlrev_b64 v[134:135], 11, v[128:129]
	v_add_u32_e32 v228, 16, v128
	v_lshl_add_u64 v[134:135], v[132:133], 0, v[134:135]
	v_ashrrev_i32_e32 v229, 31, v228
	global_load_dwordx4 v[200:203], v[134:135], off
	global_load_dwordx4 v[204:207], v[134:135], off offset:256
	v_lshlrev_b64 v[134:135], 11, v[228:229]
	v_lshl_add_u64 v[134:135], v[132:133], 0, v[134:135]
	global_load_dwordx4 v[208:211], v[134:135], off
	v_add_u32_e32 v192, 32, v128
	v_ashrrev_i32_e32 v193, 31, v192
	global_load_dwordx4 v[212:215], v[134:135], off offset:256
	v_lshlrev_b64 v[182:183], 2, v[130:131]
	v_lshlrev_b64 v[130:131], 11, v[192:193]
	v_lshl_add_u64 v[130:131], v[132:133], 0, v[130:131]
	global_load_dwordx4 v[216:219], v[130:131], off
	v_add_u32_e32 v190, 48, v128
	v_add_u32_e32 v188, 0x80, v128
	v_add_u32_e32 v186, 0x90, v128
	v_add_u32_e32 v184, 0xa0, v128
	v_add_u32_e32 v180, 0xb0, v128
	v_ashrrev_i32_e32 v191, 31, v190
	v_ashrrev_i32_e32 v189, 31, v188
	v_ashrrev_i32_e32 v187, 31, v186
	v_ashrrev_i32_e32 v185, 31, v184
	v_ashrrev_i32_e32 v181, 31, v180
	v_lshlrev_b64 v[128:129], 12, v[128:129]
	v_lshlrev_b64 v[134:135], 11, v[190:191]
	v_lshlrev_b64 v[136:137], 11, v[188:189]
	v_lshlrev_b64 v[138:139], 11, v[186:187]
	v_lshlrev_b64 v[140:141], 11, v[184:185]
	v_lshlrev_b64 v[142:143], 11, v[180:181]
	v_lshl_add_u64 v[128:129], s[6:7], 0, v[128:129]
	v_lshl_add_u64 v[134:135], v[132:133], 0, v[134:135]
	v_lshl_add_u64 v[136:137], v[132:133], 0, v[136:137]
	v_lshl_add_u64 v[138:139], v[132:133], 0, v[138:139]
	v_lshl_add_u64 v[230:231], v[132:133], 0, v[140:141]
	v_lshl_add_u64 v[232:233], v[132:133], 0, v[142:143]
	v_lshl_add_u64 v[234:235], v[128:129], 0, v[182:183]
	global_load_dwordx4 v[220:223], v[130:131], off offset:256
	global_load_dwordx4 v[224:227], v[134:135], off
	global_load_dwordx4 v[160:163], v[134:135], off offset:256
	global_load_dwordx4 v[156:159], v[136:137], off
	global_load_dwordx4 v[152:155], v[136:137], off offset:256
	global_load_dwordx4 v[148:151], v[138:139], off
	global_load_dwordx4 v[144:147], v[138:139], off offset:256
	global_load_dwordx4 v[140:143], v[230:231], off
	s_nop 0
	global_load_dwordx4 v[136:139], v[230:231], off offset:256
	global_load_dwordx4 v[132:135], v[232:233], off
	global_load_dwordx4 v[128:131], v[232:233], off offset:256
	s_and_b64 vcc, exec, s[0:1]
	s_mov_b64 s[0:1], -1
	s_waitcnt vmcnt(0)
	v_lshlrev_b32_e32 v230, 16, v200
	v_and_b32_e32 v231, 0xffff0000, v200
	v_lshlrev_b32_e32 v200, 16, v201
	v_and_b32_e32 v201, 0xffff0000, v201
	v_lshlrev_b32_e32 v238, 16, v206
	v_and_b32_e32 v239, 0xffff0000, v206
	v_lshlrev_b32_e32 v232, 16, v202
	v_and_b32_e32 v233, 0xffff0000, v202
	v_lshlrev_b32_e32 v202, 16, v203
	v_and_b32_e32 v203, 0xffff0000, v203
	v_lshlrev_b32_e32 v236, 16, v204
	v_and_b32_e32 v237, 0xffff0000, v204
	v_lshlrev_b32_e32 v204, 16, v205
	v_and_b32_e32 v205, 0xffff0000, v205
	v_lshlrev_b32_e32 v206, 16, v207
	v_and_b32_e32 v207, 0xffff0000, v207
	v_pk_add_f32 v[126:127], v[126:127], v[200:201]
	v_pk_add_f32 v[124:125], v[124:125], v[230:231]
	v_pk_add_f32 v[108:109], v[108:109], v[238:239]
	v_pk_add_f32 v[122:123], v[122:123], v[202:203]
	v_pk_add_f32 v[120:121], v[120:121], v[232:233]
	v_pk_add_f32 v[118:119], v[118:119], v[204:205]
	v_pk_add_f32 v[116:117], v[116:117], v[236:237]
	v_pk_add_f32 v[110:111], v[110:111], v[206:207]
	global_store_dwordx4 v[234:235], v[124:127], off nt
	global_store_dwordx4 v[234:235], v[120:123], off offset:16 nt
	global_store_dwordx4 v[234:235], v[116:119], off offset:512 nt
	global_store_dwordx4 v[234:235], v[108:111], off offset:528 nt
	s_nop 0
	v_lshlrev_b32_e32 v116, 16, v210
	v_lshlrev_b32_e32 v108, 16, v208
	v_and_b32_e32 v109, 0xffff0000, v208
	v_pk_add_f32 v[108:109], v[112:113], v[108:109]
	v_lshlrev_b64 v[112:113], 12, v[228:229]
	v_lshlrev_b32_e32 v110, 16, v209
	v_and_b32_e32 v111, 0xffff0000, v209
	v_and_b32_e32 v117, 0xffff0000, v210
	v_lshlrev_b32_e32 v118, 16, v211
	v_and_b32_e32 v119, 0xffff0000, v211
	v_lshl_add_u64 v[112:113], s[6:7], 0, v[112:113]
	v_pk_add_f32 v[110:111], v[114:115], v[110:111]
	v_pk_add_f32 v[106:107], v[106:107], v[118:119]
	v_pk_add_f32 v[104:105], v[104:105], v[116:117]
	v_lshl_add_u64 v[112:113], v[112:113], 0, v[182:183]
	global_store_dwordx4 v[112:113], v[108:111], off nt
	global_store_dwordx4 v[112:113], v[104:107], off offset:16 nt
	s_nop 0
	v_lshlrev_b32_e32 v108, 16, v214
	v_lshlrev_b32_e32 v104, 16, v212
	v_and_b32_e32 v105, 0xffff0000, v212
	v_lshlrev_b32_e32 v106, 16, v213
	v_and_b32_e32 v107, 0xffff0000, v213
	v_and_b32_e32 v109, 0xffff0000, v214
	v_lshlrev_b32_e32 v110, 16, v215
	v_and_b32_e32 v111, 0xffff0000, v215
	v_pk_add_f32 v[102:103], v[102:103], v[106:107]
	v_pk_add_f32 v[100:101], v[100:101], v[104:105]
	v_pk_add_f32 v[92:93], v[92:93], v[108:109]
	v_pk_add_f32 v[94:95], v[94:95], v[110:111]
	global_store_dwordx4 v[112:113], v[100:103], off offset:512 nt
	global_store_dwordx4 v[112:113], v[92:95], off offset:528 nt
	s_nop 0
	v_lshlrev_b32_e32 v100, 16, v218
	v_lshlrev_b32_e32 v92, 16, v216
	v_and_b32_e32 v93, 0xffff0000, v216
	v_pk_add_f32 v[92:93], v[96:97], v[92:93]
	v_lshlrev_b64 v[96:97], 12, v[192:193]
	v_lshlrev_b32_e32 v94, 16, v217
	v_and_b32_e32 v95, 0xffff0000, v217
	v_and_b32_e32 v101, 0xffff0000, v218
	v_lshlrev_b32_e32 v102, 16, v219
	v_and_b32_e32 v103, 0xffff0000, v219
	v_lshl_add_u64 v[96:97], s[6:7], 0, v[96:97]
	v_pk_add_f32 v[94:95], v[98:99], v[94:95]
	v_pk_add_f32 v[90:91], v[90:91], v[102:103]
	v_pk_add_f32 v[88:89], v[88:89], v[100:101]
	v_lshl_add_u64 v[96:97], v[96:97], 0, v[182:183]
	global_store_dwordx4 v[96:97], v[92:95], off nt
	global_store_dwordx4 v[96:97], v[88:91], off offset:16 nt
	s_nop 0
	v_lshlrev_b32_e32 v92, 16, v222
	v_lshlrev_b32_e32 v88, 16, v220
	v_and_b32_e32 v89, 0xffff0000, v220
	v_lshlrev_b32_e32 v90, 16, v221
	v_and_b32_e32 v91, 0xffff0000, v221
	v_and_b32_e32 v93, 0xffff0000, v222
	v_lshlrev_b32_e32 v94, 16, v223
	v_and_b32_e32 v95, 0xffff0000, v223
	v_pk_add_f32 v[86:87], v[86:87], v[90:91]
	v_pk_add_f32 v[84:85], v[84:85], v[88:89]
	v_pk_add_f32 v[76:77], v[76:77], v[92:93]
	v_pk_add_f32 v[78:79], v[78:79], v[94:95]
	global_store_dwordx4 v[96:97], v[84:87], off offset:512 nt
	global_store_dwordx4 v[96:97], v[76:79], off offset:528 nt
	s_nop 0
	v_lshlrev_b32_e32 v84, 16, v226
	v_lshlrev_b32_e32 v76, 16, v224
	v_and_b32_e32 v77, 0xffff0000, v224
	v_pk_add_f32 v[76:77], v[80:81], v[76:77]
	v_lshlrev_b64 v[80:81], 12, v[190:191]
	v_lshlrev_b32_e32 v78, 16, v225
	v_and_b32_e32 v79, 0xffff0000, v225
	v_and_b32_e32 v85, 0xffff0000, v226
	v_lshlrev_b32_e32 v86, 16, v227
	v_and_b32_e32 v87, 0xffff0000, v227
	v_lshl_add_u64 v[80:81], s[6:7], 0, v[80:81]
	v_pk_add_f32 v[78:79], v[82:83], v[78:79]
	v_pk_add_f32 v[74:75], v[74:75], v[86:87]
	v_pk_add_f32 v[72:73], v[72:73], v[84:85]
	v_lshl_add_u64 v[80:81], v[80:81], 0, v[182:183]
	global_store_dwordx4 v[80:81], v[76:79], off nt
	global_store_dwordx4 v[80:81], v[72:75], off offset:16 nt
	s_nop 0
	v_lshlrev_b32_e32 v76, 16, v162
	v_lshlrev_b32_e32 v72, 16, v160
	v_and_b32_e32 v73, 0xffff0000, v160
	v_lshlrev_b32_e32 v74, 16, v161
	v_and_b32_e32 v75, 0xffff0000, v161
	v_and_b32_e32 v77, 0xffff0000, v162
	v_lshlrev_b32_e32 v78, 16, v163
	v_and_b32_e32 v79, 0xffff0000, v163
	v_pk_add_f32 v[70:71], v[70:71], v[74:75]
	v_pk_add_f32 v[68:69], v[68:69], v[72:73]
	v_pk_add_f32 v[64:65], v[64:65], v[76:77]
	v_pk_add_f32 v[66:67], v[66:67], v[78:79]
	global_store_dwordx4 v[80:81], v[68:71], off offset:512 nt
	global_store_dwordx4 v[80:81], v[64:67], off offset:528 nt
	s_nop 0
	v_lshlrev_b32_e32 v68, 16, v158
	v_lshlrev_b32_e32 v64, 16, v156
	v_and_b32_e32 v65, 0xffff0000, v156
	v_pk_add_f32 v[60:61], v[60:61], v[64:65]
	v_lshlrev_b64 v[64:65], 12, v[188:189]
	v_lshlrev_b32_e32 v66, 16, v157
	v_and_b32_e32 v67, 0xffff0000, v157
	v_and_b32_e32 v69, 0xffff0000, v158
	v_lshlrev_b32_e32 v70, 16, v159
	v_and_b32_e32 v71, 0xffff0000, v159
	v_lshl_add_u64 v[64:65], s[6:7], 0, v[64:65]
	v_pk_add_f32 v[62:63], v[62:63], v[66:67]
	v_pk_add_f32 v[58:59], v[58:59], v[70:71]
	v_pk_add_f32 v[56:57], v[56:57], v[68:69]
	v_lshl_add_u64 v[64:65], v[64:65], 0, v[182:183]
	global_store_dwordx4 v[64:65], v[60:63], off nt
	global_store_dwordx4 v[64:65], v[56:59], off offset:16 nt
	s_nop 0
	v_lshlrev_b32_e32 v60, 16, v154
	v_lshlrev_b32_e32 v56, 16, v152
	v_and_b32_e32 v57, 0xffff0000, v152
	v_lshlrev_b32_e32 v58, 16, v153
	v_and_b32_e32 v59, 0xffff0000, v153
	v_and_b32_e32 v61, 0xffff0000, v154
	v_lshlrev_b32_e32 v62, 16, v155
	v_and_b32_e32 v63, 0xffff0000, v155
	v_pk_add_f32 v[54:55], v[54:55], v[58:59]
	v_pk_add_f32 v[52:53], v[52:53], v[56:57]
	v_pk_add_f32 v[44:45], v[44:45], v[60:61]
	v_pk_add_f32 v[46:47], v[46:47], v[62:63]
	global_store_dwordx4 v[64:65], v[52:55], off offset:512 nt
	global_store_dwordx4 v[64:65], v[44:47], off offset:528 nt
	s_nop 0
	v_lshlrev_b32_e32 v52, 16, v150
	v_lshlrev_b32_e32 v44, 16, v148
	v_and_b32_e32 v45, 0xffff0000, v148
	v_pk_add_f32 v[44:45], v[48:49], v[44:45]
	v_lshlrev_b64 v[48:49], 12, v[186:187]
	v_lshlrev_b32_e32 v46, 16, v149
	v_and_b32_e32 v47, 0xffff0000, v149
	v_and_b32_e32 v53, 0xffff0000, v150
	v_lshlrev_b32_e32 v54, 16, v151
	v_and_b32_e32 v55, 0xffff0000, v151
	v_lshl_add_u64 v[48:49], s[6:7], 0, v[48:49]
	v_pk_add_f32 v[46:47], v[50:51], v[46:47]
	v_pk_add_f32 v[42:43], v[42:43], v[54:55]
	v_pk_add_f32 v[40:41], v[40:41], v[52:53]
	v_lshl_add_u64 v[48:49], v[48:49], 0, v[182:183]
	global_store_dwordx4 v[48:49], v[44:47], off nt
	global_store_dwordx4 v[48:49], v[40:43], off offset:16 nt
	s_nop 0
	v_lshlrev_b32_e32 v44, 16, v146
	v_lshlrev_b32_e32 v40, 16, v144
	v_and_b32_e32 v41, 0xffff0000, v144
	v_lshlrev_b32_e32 v42, 16, v145
	v_and_b32_e32 v43, 0xffff0000, v145
	v_and_b32_e32 v45, 0xffff0000, v146
	v_lshlrev_b32_e32 v46, 16, v147
	v_and_b32_e32 v47, 0xffff0000, v147
	v_pk_add_f32 v[38:39], v[38:39], v[42:43]
	v_pk_add_f32 v[36:37], v[36:37], v[40:41]
	v_pk_add_f32 v[28:29], v[28:29], v[44:45]
	v_pk_add_f32 v[30:31], v[30:31], v[46:47]
	global_store_dwordx4 v[48:49], v[36:39], off offset:512 nt
	global_store_dwordx4 v[48:49], v[28:31], off offset:528 nt
	s_nop 0
	v_lshlrev_b32_e32 v36, 16, v142
	v_lshlrev_b32_e32 v28, 16, v140
	v_and_b32_e32 v29, 0xffff0000, v140
	v_pk_add_f32 v[28:29], v[32:33], v[28:29]
	v_lshlrev_b64 v[32:33], 12, v[184:185]
	v_lshlrev_b32_e32 v30, 16, v141
	v_and_b32_e32 v31, 0xffff0000, v141
	v_and_b32_e32 v37, 0xffff0000, v142
	v_lshlrev_b32_e32 v38, 16, v143
	v_and_b32_e32 v39, 0xffff0000, v143
	v_lshl_add_u64 v[32:33], s[6:7], 0, v[32:33]
	v_pk_add_f32 v[30:31], v[34:35], v[30:31]
	v_pk_add_f32 v[26:27], v[26:27], v[38:39]
	v_pk_add_f32 v[24:25], v[24:25], v[36:37]
	v_lshl_add_u64 v[32:33], v[32:33], 0, v[182:183]
	global_store_dwordx4 v[32:33], v[28:31], off nt
	global_store_dwordx4 v[32:33], v[24:27], off offset:16 nt
	s_nop 0
	v_lshlrev_b32_e32 v28, 16, v138
	v_lshlrev_b32_e32 v24, 16, v136
	v_and_b32_e32 v25, 0xffff0000, v136
	v_lshlrev_b32_e32 v26, 16, v137
	v_and_b32_e32 v27, 0xffff0000, v137
	v_and_b32_e32 v29, 0xffff0000, v138
	v_lshlrev_b32_e32 v30, 16, v139
	v_and_b32_e32 v31, 0xffff0000, v139
	v_pk_add_f32 v[22:23], v[22:23], v[26:27]
	v_pk_add_f32 v[20:21], v[20:21], v[24:25]
	v_pk_add_f32 v[12:13], v[12:13], v[28:29]
	v_pk_add_f32 v[14:15], v[14:15], v[30:31]
	global_store_dwordx4 v[32:33], v[20:23], off offset:512 nt
	global_store_dwordx4 v[32:33], v[12:15], off offset:528 nt
	s_nop 0
	v_lshlrev_b32_e32 v20, 16, v134
	v_lshlrev_b32_e32 v12, 16, v132
	v_and_b32_e32 v13, 0xffff0000, v132
	v_pk_add_f32 v[12:13], v[16:17], v[12:13]
	v_lshlrev_b64 v[16:17], 12, v[180:181]
	v_lshlrev_b32_e32 v14, 16, v133
	v_and_b32_e32 v15, 0xffff0000, v133
	v_and_b32_e32 v21, 0xffff0000, v134
	v_lshlrev_b32_e32 v22, 16, v135
	v_and_b32_e32 v23, 0xffff0000, v135
	v_lshl_add_u64 v[16:17], s[6:7], 0, v[16:17]
	v_pk_add_f32 v[14:15], v[18:19], v[14:15]
	v_pk_add_f32 v[10:11], v[10:11], v[22:23]
	v_pk_add_f32 v[8:9], v[8:9], v[20:21]
	v_lshl_add_u64 v[16:17], v[16:17], 0, v[182:183]
	global_store_dwordx4 v[16:17], v[12:15], off nt
	global_store_dwordx4 v[16:17], v[8:11], off offset:16 nt
	s_nop 0
	v_lshlrev_b32_e32 v12, 16, v130
	v_lshlrev_b32_e32 v8, 16, v128
	v_and_b32_e32 v9, 0xffff0000, v128
	v_lshlrev_b32_e32 v10, 16, v129
	v_and_b32_e32 v11, 0xffff0000, v129
	v_and_b32_e32 v13, 0xffff0000, v130
	v_lshlrev_b32_e32 v14, 16, v131
	v_and_b32_e32 v15, 0xffff0000, v131
	v_pk_add_f32 v[6:7], v[6:7], v[10:11]
	v_pk_add_f32 v[4:5], v[4:5], v[8:9]
	v_pk_add_f32 v[2:3], v[2:3], v[14:15]
	v_pk_add_f32 v[0:1], v[0:1], v[12:13]
	global_store_dwordx4 v[16:17], v[4:7], off offset:512 nt
	global_store_dwordx4 v[16:17], v[0:3], off offset:528 nt
	s_cbranch_vccnz .LBB0_1261
	s_andn2_b64 vcc, exec, s[8:9]
	s_cbranch_vccnz .LBB0_1260
	s_barrier
	s_branch .LBB0_1260
